# second workgroup barrier per decode block (before the P.V pass) to keep the 8 waves of a workgroup closer together
# speedup vs baseline: 1.0068x; 1.0068x over previous
; __device__ __forceinline__ void sb_decode_stream(Frame& F, unsigned* qctr, int base, int limit) {
;     ...
;         const float z = __builtin_bit_cast(float, zi);
;         const float e = __builtin_amdgcn_exp2f(-(z * k1 + k2));
;         const float be = __builtin_amdgcn_rcpf(1.0f + e), m = 1.0f - be;
;         float s = m;
; #pragma unroll
;         for (int o = 1; o < 64; o <<= 1) { const float t = __shfl_down(s, o); if (lane + o < 64) s *= t; }
;         const float tot = __shfl(s, 0);
;         const float sx = __shfl_down(s, 1);
;         const float a = be * (lane < 63 ? sx : 1.0f);
;         int itn = (int)(__builtin_amdgcn_readfirstlane(vn) >> 6); const bool more = itn < limit; itn = more ? itn + base : it;
;         const int bn = itn >> 11, hn = itn & 7, p0n = ((itn >> 3) & 255) * 64;
;         const int pagen = PT[bn * NPAGES + (p0n >> 7)];
;         const size_t cbn = (((size_t)pagen * PAGE + (p0n & 127)) * NH + hn) * HD + lo;
;         const size_t stepn = more ? (size_t)(NH * HD) : 0;
.Ldqa_sh2:
	s_barrier
	ds_read_b32 v201, v200
	s_xor_b32 s37, s37, 4
	s_waitcnt lgkmcnt(0)
	v_readfirstlane_b32 s2, v201
	s_nop 0
	s_lshr_b32 s73, s2, 6
	s_cmp_lt_u32 s73, 0x1800
	s_cselect_b32 s31, 1, 0
	s_add_u32 s73, s73, s94
	s_min_u32 s73, s73, 0x17ff
	s_cmp_eq_u32 s31, 1
	s_cselect_b32 s73, s73, s72
	s_lshr_b32 s6, s73, 11
	s_and_b32 s7, s73, 7
	s_bfe_u32 s8, s73, 0x80003
	s_lshl_b32 s9, s6, 7
	s_lshr_b32 s10, s8, 1
	s_or_b32 s9, s9, s10
	s_lshl_b32 s9, s9, 2
	s_lshl_b32 s10, s7, 2
	s_load_dword s29, s[54:55], s9
	s_load_dword s30, s[56:57], s10
	v_add_f32_dpp v132, v132, v132 row_ror:8 row_mask:0xf bank_mask:0x3
	v_add_f32_dpp v133, v133, v133 row_ror:8 row_mask:0xf bank_mask:0x3
	v_add_f32_dpp v134, v134, v134 row_ror:8 row_mask:0xf bank_mask:0x3
	v_add_f32_dpp v135, v135, v135 row_ror:8 row_mask:0xf bank_mask:0x3
	v_add_f32_dpp v136, v136, v136 row_ror:8 row_mask:0xf bank_mask:0x3
	v_add_f32_dpp v137, v137, v137 row_ror:8 row_mask:0xf bank_mask:0x3
	v_add_f32_dpp v138, v138, v138 row_ror:8 row_mask:0xf bank_mask:0x3
	v_add_f32_dpp v139, v139, v139 row_ror:8 row_mask:0xf bank_mask:0x3
	v_add_f32_dpp v132, v140, v140 row_ror:8 row_mask:0xf bank_mask:0xc
	v_add_f32_dpp v133, v141, v141 row_ror:8 row_mask:0xf bank_mask:0xc
	v_add_f32_dpp v134, v142, v142 row_ror:8 row_mask:0xf bank_mask:0xc
	v_add_f32_dpp v135, v143, v143 row_ror:8 row_mask:0xf bank_mask:0xc
	v_add_f32_dpp v136, v144, v144 row_ror:8 row_mask:0xf bank_mask:0xc
	v_add_f32_dpp v137, v145, v145 row_ror:8 row_mask:0xf bank_mask:0xc
	v_add_f32_dpp v138, v146, v146 row_ror:8 row_mask:0xf bank_mask:0xc
	v_add_f32_dpp v139, v147, v147 row_ror:8 row_mask:0xf bank_mask:0xc
	v_add_f32_dpp v132, v132, v132 row_ror:12 row_mask:0xf bank_mask:0x5
	v_add_f32_dpp v133, v133, v133 row_ror:12 row_mask:0xf bank_mask:0x5
	v_add_f32_dpp v134, v134, v134 row_ror:12 row_mask:0xf bank_mask:0x5
	v_add_f32_dpp v135, v135, v135 row_ror:12 row_mask:0xf bank_mask:0x5
	v_add_f32_dpp v132, v136, v136 row_ror:4 row_mask:0xf bank_mask:0xa
	v_add_f32_dpp v133, v137, v137 row_ror:4 row_mask:0xf bank_mask:0xa
	v_add_f32_dpp v134, v138, v138 row_ror:4 row_mask:0xf bank_mask:0xa
	v_add_f32_dpp v135, v139, v139 row_ror:4 row_mask:0xf bank_mask:0xa
	v_add_f32_dpp v140, v132, v132 quad_perm:[2,3,0,1] row_mask:0xf bank_mask:0xf
	v_add_f32_dpp v142, v134, v134 quad_perm:[2,3,0,1] row_mask:0xf bank_mask:0xf
	v_add_f32_dpp v141, v133, v133 quad_perm:[2,3,0,1] row_mask:0xf bank_mask:0xf
	v_add_f32_dpp v143, v135, v135 quad_perm:[2,3,0,1] row_mask:0xf bank_mask:0xf
	v_cndmask_b32_e64 v132, v140, v142, s[76:77]
	v_cndmask_b32_e64 v133, v141, v143, s[76:77]
	s_nop 0
	v_add_f32_dpp v196, v132, v132 quad_perm:[1,0,3,2] row_mask:0xf bank_mask:0xf
	v_add_f32_dpp v197, v133, v133 quad_perm:[1,0,3,2] row_mask:0xf bank_mask:0xf
	v_cndmask_b32_e64 v177, v196, v197, s[78:79]
	s_nop 1
	v_permlane16_swap_b32_e32 v176, v177
	v_add_f32_e32 v178, v176, v177
	v_mul_f32_e32 v178, 0x3e0293ee, v178
	v_add_f32_e32 v178, v178, v192
	v_exp_f32_e64 v198, -v178
	s_nop 0
	v_add_f32_e32 v198, 1.0, v198
	v_rcp_f32_e32 v179, v198
	s_nop 0
	v_sub_f32_e32 v180, 1.0, v179
	v_mov_b32_e32 v181, v180
	s_nop 1
	v_permlane32_swap_b32_e32 v180, v181
	v_mul_f32_e32 v183, v180, v181
	s_nop 1
	v_mul_f32_dpp v183, v183, v183 row_shl:1 row_mask:0xf bank_mask:0xf
	s_nop 1
	v_mul_f32_dpp v183, v183, v183 row_shl:2 row_mask:0xf bank_mask:0xf
	s_nop 1
	v_mul_f32_dpp v183, v183, v183 row_shl:4 row_mask:0xf bank_mask:0xf
	s_nop 1
	v_mul_f32_dpp v183, v183, v183 row_shl:8 row_mask:0xf bank_mask:0xf
	s_nop 0
	v_readlane_b32 s33, v183, 16
	v_mov_b32_e32 v184, 1.0
	s_nop 0
	v_mov_b32_e32 v185, s33
	s_nop 1
	v_mul_f32_dpp v183, v183, v185 quad_perm:[0,1,2,3] row_mask:0x5 bank_mask:0xf
	v_mov_b32_dpp v184, v185 quad_perm:[0,1,2,3] row_mask:0x5 bank_mask:0xf
	s_nop 1
	v_mov_b32_dpp v184, v183 row_shl:1 row_mask:0xf bank_mask:0xf
	v_mul_f32_e32 v186, v179, v184
	s_nop 1
	v_mul_f32_dpp v186, v186, v181 quad_perm:[0,1,2,3] row_mask:0x3 bank_mask:0xf
	s_cmp_eq_u32 s31, 0
	s_cbranch_scc1 .Ldqa_tail
	s_waitcnt lgkmcnt(0)
	s_mov_b32 s12, s29
	s_mov_b32 s13, 0
	s_lshl_b64 s[12:13], s[12:13], 19
	s_and_b32 s14, s8, 1
	s_lshl_b32 s14, s14, 18
	s_lshl_b32 s15, s7, 9
	s_or_b32 s14, s14, s15
	s_or_b32 s80, s12, s14
	s_mov_b32 s81, s13
	s_add_u32 s64, s50, s80
	s_addc_u32 s65, s51, s81
	s_mul_i32 s16, s6, 0x7040
	s_add_u32 s16, s16, s15
	s_add_u32 s16, s60, s16
	s_addc_u32 s17, s61, 0
	global_load_dwordx4 v[156:159], v193, s[16:17]
	s_barrier
; __device__ __forceinline__ void sb_decode_stream(Frame& F, unsigned* qctr, int base, int limit) {
;     ...
;         f32x4 o4 = {0.f, 0.f, 0.f, 0.f};
; #pragma unroll
;         for (int i = 0; i < 16; ++i) { const float aj = __shfl(a, 2 * i + half); o4 += aj * A[i]; }
;         const f32x4 q4n = *(const f32x4*)(SSP(S_PROJ) + (size_t)bn * IN_COLS + hn * HD + 4 * l32);
; #pragma unroll
;         for (int i = 0; i < 16; ++i) A[i] = __builtin_nontemporal_load((const f32x4*)(CK + cbn + (size_t)(2 * i) * stepn));
; #pragma unroll
;         for (int i = 0; i < 16; ++i) { const float aj = __shfl(a, 32 + 2 * i + half); o4 += aj * B[i]; }
; #pragma unroll
;         for (int i = 0; i < 16; ++i) B[i] = __builtin_nontemporal_load((const f32x4*)(CK + cbn + (size_t)(32 + 2 * i) * stepn));
	v_mov_b32_e32 v160, 0
	v_mov_b32_e32 v161, 0
	v_mov_b32_e32 v162, 0
	v_mov_b32_e32 v163, 0
	v_mov_b32_e32 v164, 0
	v_mov_b32_e32 v165, 0
	v_mov_b32_e32 v166, 0
	v_mov_b32_e32 v167, 0
	ds_bpermute_b32 v168, v188, v186 offset:0
	ds_bpermute_b32 v170, v188, v186 offset:4
	ds_bpermute_b32 v172, v188, v186 offset:8
	ds_bpermute_b32 v174, v188, v186 offset:12
	s_waitcnt vmcnt(32) lgkmcnt(3)
	v_pk_fma_f32 v[160:161], v[4:5], v[168:169], v[160:161] op_sel_hi:[1,0,1]
	v_pk_fma_f32 v[162:163], v[6:7], v[168:169], v[162:163] op_sel_hi:[1,0,1]
	global_load_dwordx4 v[4:7], v187, s[64:65] nt
	s_add_u32 s64, s64, 0x2000
	s_addc_u32 s65, s65, 0
	ds_bpermute_b32 v168, v188, v186 offset:16
	s_waitcnt vmcnt(32) lgkmcnt(3)
	v_pk_fma_f32 v[164:165], v[8:9], v[170:171], v[164:165] op_sel_hi:[1,0,1]
	v_pk_fma_f32 v[166:167], v[10:11], v[170:171], v[166:167] op_sel_hi:[1,0,1]
	global_load_dwordx4 v[8:11], v187, s[64:65] nt
	s_add_u32 s64, s64, 0x2000
	s_addc_u32 s65, s65, 0
	ds_bpermute_b32 v170, v188, v186 offset:20
	s_waitcnt vmcnt(32) lgkmcnt(3)
	v_pk_fma_f32 v[160:161], v[12:13], v[172:173], v[160:161] op_sel_hi:[1,0,1]
	v_pk_fma_f32 v[162:163], v[14:15], v[172:173], v[162:163] op_sel_hi:[1,0,1]
	global_load_dwordx4 v[12:15], v187, s[64:65] nt
	s_add_u32 s64, s64, 0x2000
	s_addc_u32 s65, s65, 0
	ds_bpermute_b32 v172, v188, v186 offset:24
	s_waitcnt vmcnt(32) lgkmcnt(3)
	v_pk_fma_f32 v[164:165], v[16:17], v[174:175], v[164:165] op_sel_hi:[1,0,1]
	v_pk_fma_f32 v[166:167], v[18:19], v[174:175], v[166:167] op_sel_hi:[1,0,1]
	global_load_dwordx4 v[16:19], v187, s[64:65] nt
	s_add_u32 s64, s64, 0x2000
	s_addc_u32 s65, s65, 0
	ds_bpermute_b32 v174, v188, v186 offset:28
	s_waitcnt vmcnt(32) lgkmcnt(3)
	v_pk_fma_f32 v[160:161], v[20:21], v[168:169], v[160:161] op_sel_hi:[1,0,1]
	v_pk_fma_f32 v[162:163], v[22:23], v[168:169], v[162:163] op_sel_hi:[1,0,1]
	global_load_dwordx4 v[20:23], v187, s[64:65] nt
	s_add_u32 s64, s64, 0x2000
	s_addc_u32 s65, s65, 0
	ds_bpermute_b32 v168, v188, v186 offset:32
	s_waitcnt vmcnt(32) lgkmcnt(3)
	v_pk_fma_f32 v[164:165], v[24:25], v[170:171], v[164:165] op_sel_hi:[1,0,1]
	v_pk_fma_f32 v[166:167], v[26:27], v[170:171], v[166:167] op_sel_hi:[1,0,1]
	global_load_dwordx4 v[24:27], v187, s[64:65] nt
	s_add_u32 s64, s64, 0x2000
	s_addc_u32 s65, s65, 0
	ds_bpermute_b32 v170, v188, v186 offset:36
	s_waitcnt vmcnt(32) lgkmcnt(3)
	v_pk_fma_f32 v[160:161], v[28:29], v[172:173], v[160:161] op_sel_hi:[1,0,1]
	v_pk_fma_f32 v[162:163], v[30:31], v[172:173], v[162:163] op_sel_hi:[1,0,1]
	global_load_dwordx4 v[28:31], v187, s[64:65] nt
	s_add_u32 s64, s64, 0x2000
	s_addc_u32 s65, s65, 0
	ds_bpermute_b32 v172, v188, v186 offset:40
	s_waitcnt vmcnt(32) lgkmcnt(3)
	v_pk_fma_f32 v[164:165], v[32:33], v[174:175], v[164:165] op_sel_hi:[1,0,1]
	v_pk_fma_f32 v[166:167], v[34:35], v[174:175], v[166:167] op_sel_hi:[1,0,1]
	global_load_dwordx4 v[32:35], v187, s[64:65] nt
	s_add_u32 s64, s64, 0x2000
	s_addc_u32 s65, s65, 0
	ds_bpermute_b32 v174, v188, v186 offset:44
	s_waitcnt vmcnt(32) lgkmcnt(3)
	v_pk_fma_f32 v[160:161], v[36:37], v[168:169], v[160:161] op_sel_hi:[1,0,1]
	v_pk_fma_f32 v[162:163], v[38:39], v[168:169], v[162:163] op_sel_hi:[1,0,1]
	global_load_dwordx4 v[36:39], v187, s[64:65] nt
	s_add_u32 s64, s64, 0x2000
	s_addc_u32 s65, s65, 0
	ds_bpermute_b32 v168, v188, v186 offset:48
	s_waitcnt vmcnt(32) lgkmcnt(3)
	v_pk_fma_f32 v[164:165], v[40:41], v[170:171], v[164:165] op_sel_hi:[1,0,1]
	v_pk_fma_f32 v[166:167], v[42:43], v[170:171], v[166:167] op_sel_hi:[1,0,1]
	global_load_dwordx4 v[40:43], v187, s[64:65] nt
	s_add_u32 s64, s64, 0x2000
	s_addc_u32 s65, s65, 0
	ds_bpermute_b32 v170, v188, v186 offset:52
	s_waitcnt vmcnt(32) lgkmcnt(3)
	v_pk_fma_f32 v[160:161], v[44:45], v[172:173], v[160:161] op_sel_hi:[1,0,1]
	v_pk_fma_f32 v[162:163], v[46:47], v[172:173], v[162:163] op_sel_hi:[1,0,1]
	global_load_dwordx4 v[44:47], v187, s[64:65] nt
	s_add_u32 s64, s64, 0x2000
	s_addc_u32 s65, s65, 0
	ds_bpermute_b32 v172, v188, v186 offset:56
	s_waitcnt vmcnt(32) lgkmcnt(3)
	v_pk_fma_f32 v[164:165], v[48:49], v[174:175], v[164:165] op_sel_hi:[1,0,1]
	v_pk_fma_f32 v[166:167], v[50:51], v[174:175], v[166:167] op_sel_hi:[1,0,1]
	global_load_dwordx4 v[48:51], v187, s[64:65] nt
	s_add_u32 s64, s64, 0x2000
	s_addc_u32 s65, s65, 0
	ds_bpermute_b32 v174, v188, v186 offset:60
	s_waitcnt vmcnt(32) lgkmcnt(3)
	v_pk_fma_f32 v[160:161], v[52:53], v[168:169], v[160:161] op_sel_hi:[1,0,1]
	v_pk_fma_f32 v[162:163], v[54:55], v[168:169], v[162:163] op_sel_hi:[1,0,1]
	global_load_dwordx4 v[52:55], v187, s[64:65] nt
	s_add_u32 s64, s64, 0x2000
	s_addc_u32 s65, s65, 0
	ds_bpermute_b32 v168, v188, v186 offset:64
	s_waitcnt vmcnt(32) lgkmcnt(3)
	v_pk_fma_f32 v[164:165], v[56:57], v[170:171], v[164:165] op_sel_hi:[1,0,1]
	v_pk_fma_f32 v[166:167], v[58:59], v[170:171], v[166:167] op_sel_hi:[1,0,1]
	global_load_dwordx4 v[56:59], v187, s[64:65] nt
	s_add_u32 s64, s64, 0x2000
	s_addc_u32 s65, s65, 0
	ds_bpermute_b32 v170, v188, v186 offset:68
	s_waitcnt vmcnt(32) lgkmcnt(3)
	v_pk_fma_f32 v[160:161], v[60:61], v[172:173], v[160:161] op_sel_hi:[1,0,1]
	v_pk_fma_f32 v[162:163], v[62:63], v[172:173], v[162:163] op_sel_hi:[1,0,1]
	global_load_dwordx4 v[60:63], v187, s[64:65] nt
	s_add_u32 s64, s64, 0x2000
	s_addc_u32 s65, s65, 0
	ds_bpermute_b32 v172, v188, v186 offset:72
	s_waitcnt vmcnt(32) lgkmcnt(3)
	v_pk_fma_f32 v[164:165], v[64:65], v[174:175], v[164:165] op_sel_hi:[1,0,1]
	v_pk_fma_f32 v[166:167], v[66:67], v[174:175], v[166:167] op_sel_hi:[1,0,1]
	global_load_dwordx4 v[64:67], v187, s[64:65] nt
	s_add_u32 s64, s64, 0x2000
	s_addc_u32 s65, s65, 0
	ds_bpermute_b32 v174, v188, v186 offset:76
	s_waitcnt vmcnt(32) lgkmcnt(3)
; __device__ __forceinline__ void sb_decode_stream(Frame& F, unsigned* qctr, int base, int limit) {
;     ...
;         f32x4 o4 = {0.f, 0.f, 0.f, 0.f};
; #pragma unroll
;         for (int i = 0; i < 16; ++i) { const float aj = __shfl(a, 2 * i + half); o4 += aj * A[i]; }
;         const f32x4 q4n = *(const f32x4*)(SSP(S_PROJ) + (size_t)bn * IN_COLS + hn * HD + 4 * l32);
; #pragma unroll
;         for (int i = 0; i < 16; ++i) A[i] = __builtin_nontemporal_load((const f32x4*)(CK + cbn + (size_t)(2 * i) * stepn));
; #pragma unroll
;         for (int i = 0; i < 16; ++i) { const float aj = __shfl(a, 32 + 2 * i + half); o4 += aj * B[i]; }
; #pragma unroll
;         for (int i = 0; i < 16; ++i) B[i] = __builtin_nontemporal_load((const f32x4*)(CK + cbn + (size_t)(32 + 2 * i) * stepn));
;         o4.x += __shfl_xor(o4.x, 32); o4.y += __shfl_xor(o4.y, 32); o4.z += __shfl_xor(o4.z, 32); o4.w += __shfl_xor(o4.w, 32);
;         float* P = SSP(S_PART) + ((size_t)bh * DSEG + blk) * DPART;
;         if (half == 0) *(f32x4*)(P + 4 * l32) = o4; if (lane == 0) P[128] = tot;
;         if (!more) break;
;         it = itn; cb = cbn; q4 = q4n;
	v_pk_fma_f32 v[160:161], v[68:69], v[168:169], v[160:161] op_sel_hi:[1,0,1]
	v_pk_fma_f32 v[162:163], v[70:71], v[168:169], v[162:163] op_sel_hi:[1,0,1]
	global_load_dwordx4 v[68:71], v187, s[64:65] nt
	s_add_u32 s64, s64, 0x2000
	s_addc_u32 s65, s65, 0
	ds_bpermute_b32 v168, v188, v186 offset:80
	s_waitcnt vmcnt(32) lgkmcnt(3)
	v_pk_fma_f32 v[164:165], v[72:73], v[170:171], v[164:165] op_sel_hi:[1,0,1]
	v_pk_fma_f32 v[166:167], v[74:75], v[170:171], v[166:167] op_sel_hi:[1,0,1]
	global_load_dwordx4 v[72:75], v187, s[64:65] nt
	s_add_u32 s64, s64, 0x2000
	s_addc_u32 s65, s65, 0
	ds_bpermute_b32 v170, v188, v186 offset:84
	s_waitcnt vmcnt(32) lgkmcnt(3)
	v_pk_fma_f32 v[160:161], v[76:77], v[172:173], v[160:161] op_sel_hi:[1,0,1]
	v_pk_fma_f32 v[162:163], v[78:79], v[172:173], v[162:163] op_sel_hi:[1,0,1]
	global_load_dwordx4 v[76:79], v187, s[64:65] nt
	s_add_u32 s64, s64, 0x2000
	s_addc_u32 s65, s65, 0
	ds_bpermute_b32 v172, v188, v186 offset:88
	s_waitcnt vmcnt(32) lgkmcnt(3)
	v_pk_fma_f32 v[164:165], v[80:81], v[174:175], v[164:165] op_sel_hi:[1,0,1]
	v_pk_fma_f32 v[166:167], v[82:83], v[174:175], v[166:167] op_sel_hi:[1,0,1]
	global_load_dwordx4 v[80:83], v187, s[64:65] nt
	s_add_u32 s64, s64, 0x2000
	s_addc_u32 s65, s65, 0
	ds_bpermute_b32 v174, v188, v186 offset:92
	s_waitcnt vmcnt(32) lgkmcnt(3)
	v_pk_fma_f32 v[160:161], v[84:85], v[168:169], v[160:161] op_sel_hi:[1,0,1]
	v_pk_fma_f32 v[162:163], v[86:87], v[168:169], v[162:163] op_sel_hi:[1,0,1]
	global_load_dwordx4 v[84:87], v187, s[64:65] nt
	s_add_u32 s64, s64, 0x2000
	s_addc_u32 s65, s65, 0
	ds_bpermute_b32 v168, v188, v186 offset:96
	s_waitcnt vmcnt(32) lgkmcnt(3)
	v_pk_fma_f32 v[164:165], v[88:89], v[170:171], v[164:165] op_sel_hi:[1,0,1]
	v_pk_fma_f32 v[166:167], v[90:91], v[170:171], v[166:167] op_sel_hi:[1,0,1]
	global_load_dwordx4 v[88:91], v187, s[64:65] nt
	s_add_u32 s64, s64, 0x2000
	s_addc_u32 s65, s65, 0
	ds_bpermute_b32 v170, v188, v186 offset:100
	s_waitcnt vmcnt(32) lgkmcnt(3)
	v_pk_fma_f32 v[160:161], v[92:93], v[172:173], v[160:161] op_sel_hi:[1,0,1]
	v_pk_fma_f32 v[162:163], v[94:95], v[172:173], v[162:163] op_sel_hi:[1,0,1]
	global_load_dwordx4 v[92:95], v187, s[64:65] nt
	s_add_u32 s64, s64, 0x2000
	s_addc_u32 s65, s65, 0
	ds_bpermute_b32 v172, v188, v186 offset:104
	s_waitcnt vmcnt(32) lgkmcnt(3)
	v_pk_fma_f32 v[164:165], v[96:97], v[174:175], v[164:165] op_sel_hi:[1,0,1]
	v_pk_fma_f32 v[166:167], v[98:99], v[174:175], v[166:167] op_sel_hi:[1,0,1]
	global_load_dwordx4 v[96:99], v187, s[64:65] nt
	s_add_u32 s64, s64, 0x2000
	s_addc_u32 s65, s65, 0
	ds_bpermute_b32 v174, v188, v186 offset:108
	s_waitcnt vmcnt(32) lgkmcnt(3)
	v_pk_fma_f32 v[160:161], v[100:101], v[168:169], v[160:161] op_sel_hi:[1,0,1]
	v_pk_fma_f32 v[162:163], v[102:103], v[168:169], v[162:163] op_sel_hi:[1,0,1]
	global_load_dwordx4 v[100:103], v187, s[64:65] nt
	s_add_u32 s64, s64, 0x2000
	s_addc_u32 s65, s65, 0
	ds_bpermute_b32 v168, v188, v186 offset:112
	s_waitcnt vmcnt(32) lgkmcnt(3)
	v_pk_fma_f32 v[164:165], v[104:105], v[170:171], v[164:165] op_sel_hi:[1,0,1]
	v_pk_fma_f32 v[166:167], v[106:107], v[170:171], v[166:167] op_sel_hi:[1,0,1]
	global_load_dwordx4 v[104:107], v187, s[64:65] nt
	s_add_u32 s64, s64, 0x2000
	s_addc_u32 s65, s65, 0
	ds_bpermute_b32 v170, v188, v186 offset:116
	s_waitcnt vmcnt(32) lgkmcnt(3)
	v_pk_fma_f32 v[160:161], v[108:109], v[172:173], v[160:161] op_sel_hi:[1,0,1]
	v_pk_fma_f32 v[162:163], v[110:111], v[172:173], v[162:163] op_sel_hi:[1,0,1]
	global_load_dwordx4 v[108:111], v187, s[64:65] nt
	s_add_u32 s64, s64, 0x2000
	s_addc_u32 s65, s65, 0
	ds_bpermute_b32 v172, v188, v186 offset:120
	s_waitcnt vmcnt(32) lgkmcnt(3)
	v_pk_fma_f32 v[164:165], v[112:113], v[174:175], v[164:165] op_sel_hi:[1,0,1]
	v_pk_fma_f32 v[166:167], v[114:115], v[174:175], v[166:167] op_sel_hi:[1,0,1]
	global_load_dwordx4 v[112:115], v187, s[64:65] nt
	s_add_u32 s64, s64, 0x2000
	s_addc_u32 s65, s65, 0
	ds_bpermute_b32 v174, v188, v186 offset:124
	s_waitcnt vmcnt(32) lgkmcnt(3)
	v_pk_fma_f32 v[160:161], v[116:117], v[168:169], v[160:161] op_sel_hi:[1,0,1]
	v_pk_fma_f32 v[162:163], v[118:119], v[168:169], v[162:163] op_sel_hi:[1,0,1]
	global_load_dwordx4 v[116:119], v187, s[64:65] nt
	s_add_u32 s64, s64, 0x2000
	s_addc_u32 s65, s65, 0
	s_waitcnt vmcnt(32) lgkmcnt(2)
	v_pk_fma_f32 v[164:165], v[120:121], v[170:171], v[164:165] op_sel_hi:[1,0,1]
	v_pk_fma_f32 v[166:167], v[122:123], v[170:171], v[166:167] op_sel_hi:[1,0,1]
	global_load_dwordx4 v[120:123], v187, s[64:65] nt
	s_add_u32 s64, s64, 0x2000
	s_addc_u32 s65, s65, 0
	s_waitcnt vmcnt(32) lgkmcnt(1)
	v_pk_fma_f32 v[160:161], v[124:125], v[172:173], v[160:161] op_sel_hi:[1,0,1]
	v_pk_fma_f32 v[162:163], v[126:127], v[172:173], v[162:163] op_sel_hi:[1,0,1]
	global_load_dwordx4 v[124:127], v187, s[64:65] nt
	s_add_u32 s64, s64, 0x2000
	s_addc_u32 s65, s65, 0
	s_waitcnt vmcnt(32) lgkmcnt(0)
	v_pk_fma_f32 v[164:165], v[128:129], v[174:175], v[164:165] op_sel_hi:[1,0,1]
	v_pk_fma_f32 v[166:167], v[130:131], v[174:175], v[166:167] op_sel_hi:[1,0,1]
	global_load_dwordx4 v[128:131], v187, s[64:65] nt
	s_add_u32 s64, s64, 0x2000
	s_addc_u32 s65, s65, 0
	s_nop 1
	v_pk_add_f32 v[160:161], v[160:161], v[164:165]
	v_pk_add_f32 v[162:163], v[162:163], v[166:167]
	s_nop 1
	v_mov_b32_e32 v164, v160
	v_mov_b32_e32 v165, v161
	v_mov_b32_e32 v166, v162
	v_mov_b32_e32 v167, v163
	v_permlane32_swap_b32_e32 v160, v164
	v_permlane32_swap_b32_e32 v161, v165
	v_permlane32_swap_b32_e32 v162, v166
	v_permlane32_swap_b32_e32 v163, v167
	v_pk_add_f32 v[160:161], v[160:161], v[164:165]
	v_pk_add_f32 v[162:163], v[162:163], v[166:167]
	s_nop 1
	s_mov_b32 exec_hi, 0
	global_store_dwordx4 v193, v[160:163], s[70:71]
	s_mov_b32 exec_lo, 1
	global_store_dword v189, v183, s[70:71] offset:512
	s_mov_b64 exec, -1
	s_mov_b32 s72, s73
	s_branch .Ldqa_loop

; __device__ __forceinline__ void sb_decode_stream(Frame& F, unsigned* qctr, int base, int limit) {
;     ...
;         const float z = __builtin_bit_cast(float, zi);
;         const float e = __builtin_amdgcn_exp2f(-(z * k1 + k2));
;         const float be = __builtin_amdgcn_rcpf(1.0f + e), m = 1.0f - be;
;         float s = m;
; #pragma unroll
;         for (int o = 1; o < 64; o <<= 1) { const float t = __shfl_down(s, o); if (lane + o < 64) s *= t; }
;         const float tot = __shfl(s, 0);
;         const float sx = __shfl_down(s, 1);
;         const float a = be * (lane < 63 ? sx : 1.0f);
;         int itn = (int)(__builtin_amdgcn_readfirstlane(vn) >> 6); const bool more = itn < limit; itn = more ? itn + base : it;
;         const int bn = itn >> 11, hn = itn & 7, p0n = ((itn >> 3) & 255) * 64;
;         const int pagen = PT[bn * NPAGES + (p0n >> 7)];
;         const size_t cbn = (((size_t)pagen * PAGE + (p0n & 127)) * NH + hn) * HD + lo;
;         const size_t stepn = more ? (size_t)(NH * HD) : 0;
.Ldqc_sh2:
	s_barrier
	ds_read_b32 v201, v200
	s_xor_b32 s37, s37, 4
	s_waitcnt lgkmcnt(0)
	v_readfirstlane_b32 s2, v201
	s_nop 0
	s_lshr_b32 s73, s2, 6
	s_cmp_lt_u32 s73, 0x2800
	s_cselect_b32 s31, 1, 0
	s_add_u32 s73, s73, s94
	s_min_u32 s73, s73, 0x27ff
	s_add_u32 s73, s73, 0x1800
	s_cmp_eq_u32 s31, 1
	s_cselect_b32 s73, s73, s72
	s_lshr_b32 s6, s73, 11
	s_and_b32 s7, s73, 7
	s_bfe_u32 s8, s73, 0x80003
	s_lshl_b32 s9, s6, 7
	s_lshr_b32 s10, s8, 1
	s_or_b32 s9, s9, s10
	s_lshl_b32 s9, s9, 2
	s_lshl_b32 s10, s7, 2
	s_load_dword s29, s[54:55], s9
	s_load_dword s30, s[56:57], s10
	v_add_f32_dpp v132, v132, v132 row_ror:8 row_mask:0xf bank_mask:0x3
	v_add_f32_dpp v133, v133, v133 row_ror:8 row_mask:0xf bank_mask:0x3
	v_add_f32_dpp v134, v134, v134 row_ror:8 row_mask:0xf bank_mask:0x3
	v_add_f32_dpp v135, v135, v135 row_ror:8 row_mask:0xf bank_mask:0x3
	v_add_f32_dpp v136, v136, v136 row_ror:8 row_mask:0xf bank_mask:0x3
	v_add_f32_dpp v137, v137, v137 row_ror:8 row_mask:0xf bank_mask:0x3
	v_add_f32_dpp v138, v138, v138 row_ror:8 row_mask:0xf bank_mask:0x3
	v_add_f32_dpp v139, v139, v139 row_ror:8 row_mask:0xf bank_mask:0x3
	v_add_f32_dpp v132, v140, v140 row_ror:8 row_mask:0xf bank_mask:0xc
	v_add_f32_dpp v133, v141, v141 row_ror:8 row_mask:0xf bank_mask:0xc
	v_add_f32_dpp v134, v142, v142 row_ror:8 row_mask:0xf bank_mask:0xc
	v_add_f32_dpp v135, v143, v143 row_ror:8 row_mask:0xf bank_mask:0xc
	v_add_f32_dpp v136, v144, v144 row_ror:8 row_mask:0xf bank_mask:0xc
	v_add_f32_dpp v137, v145, v145 row_ror:8 row_mask:0xf bank_mask:0xc
	v_add_f32_dpp v138, v146, v146 row_ror:8 row_mask:0xf bank_mask:0xc
	v_add_f32_dpp v139, v147, v147 row_ror:8 row_mask:0xf bank_mask:0xc
	v_add_f32_dpp v132, v132, v132 row_ror:12 row_mask:0xf bank_mask:0x5
	v_add_f32_dpp v133, v133, v133 row_ror:12 row_mask:0xf bank_mask:0x5
	v_add_f32_dpp v134, v134, v134 row_ror:12 row_mask:0xf bank_mask:0x5
	v_add_f32_dpp v135, v135, v135 row_ror:12 row_mask:0xf bank_mask:0x5
	v_add_f32_dpp v132, v136, v136 row_ror:4 row_mask:0xf bank_mask:0xa
	v_add_f32_dpp v133, v137, v137 row_ror:4 row_mask:0xf bank_mask:0xa
	v_add_f32_dpp v134, v138, v138 row_ror:4 row_mask:0xf bank_mask:0xa
	v_add_f32_dpp v135, v139, v139 row_ror:4 row_mask:0xf bank_mask:0xa
	v_add_f32_dpp v140, v132, v132 quad_perm:[2,3,0,1] row_mask:0xf bank_mask:0xf
	v_add_f32_dpp v142, v134, v134 quad_perm:[2,3,0,1] row_mask:0xf bank_mask:0xf
	v_add_f32_dpp v141, v133, v133 quad_perm:[2,3,0,1] row_mask:0xf bank_mask:0xf
	v_add_f32_dpp v143, v135, v135 quad_perm:[2,3,0,1] row_mask:0xf bank_mask:0xf
	v_cndmask_b32_e64 v132, v140, v142, s[76:77]
	v_cndmask_b32_e64 v133, v141, v143, s[76:77]
	s_nop 0
	v_add_f32_dpp v196, v132, v132 quad_perm:[1,0,3,2] row_mask:0xf bank_mask:0xf
	v_add_f32_dpp v197, v133, v133 quad_perm:[1,0,3,2] row_mask:0xf bank_mask:0xf
	v_cndmask_b32_e64 v177, v196, v197, s[78:79]
	s_nop 1
	v_permlane16_swap_b32_e32 v176, v177
	v_add_f32_e32 v178, v176, v177
	v_mul_f32_e32 v178, 0x3e0293ee, v178
	v_add_f32_e32 v178, v178, v192
	v_exp_f32_e64 v198, -v178
	s_nop 0
	v_add_f32_e32 v198, 1.0, v198
	v_rcp_f32_e32 v179, v198
	s_nop 0
	v_sub_f32_e32 v180, 1.0, v179
	v_mov_b32_e32 v181, v180
	s_nop 1
	v_permlane32_swap_b32_e32 v180, v181
	v_mul_f32_e32 v183, v180, v181
	s_nop 1
	v_mul_f32_dpp v183, v183, v183 row_shl:1 row_mask:0xf bank_mask:0xf
	s_nop 1
	v_mul_f32_dpp v183, v183, v183 row_shl:2 row_mask:0xf bank_mask:0xf
	s_nop 1
	v_mul_f32_dpp v183, v183, v183 row_shl:4 row_mask:0xf bank_mask:0xf
	s_nop 1
	v_mul_f32_dpp v183, v183, v183 row_shl:8 row_mask:0xf bank_mask:0xf
	s_nop 0
	v_readlane_b32 s33, v183, 16
	v_mov_b32_e32 v184, 1.0
	s_nop 0
	v_mov_b32_e32 v185, s33
	s_nop 1
	v_mul_f32_dpp v183, v183, v185 quad_perm:[0,1,2,3] row_mask:0x5 bank_mask:0xf
	v_mov_b32_dpp v184, v185 quad_perm:[0,1,2,3] row_mask:0x5 bank_mask:0xf
	s_nop 1
	v_mov_b32_dpp v184, v183 row_shl:1 row_mask:0xf bank_mask:0xf
	v_mul_f32_e32 v186, v179, v184
	s_nop 1
	v_mul_f32_dpp v186, v186, v181 quad_perm:[0,1,2,3] row_mask:0x3 bank_mask:0xf
	s_cmp_eq_u32 s31, 0
	s_cbranch_scc1 .Ldqc_tail
	s_waitcnt lgkmcnt(0)
	s_mov_b32 s12, s29
	s_mov_b32 s13, 0
	s_lshl_b64 s[12:13], s[12:13], 19
	s_and_b32 s14, s8, 1
	s_lshl_b32 s14, s14, 18
	s_lshl_b32 s15, s7, 9
	s_or_b32 s14, s14, s15
	s_or_b32 s80, s12, s14
	s_mov_b32 s81, s13
	s_add_u32 s64, s50, s80
	s_addc_u32 s65, s51, s81
	s_mul_i32 s16, s6, 0x7040
	s_add_u32 s16, s16, s15
	s_add_u32 s16, s60, s16
	s_addc_u32 s17, s61, 0
	global_load_dwordx4 v[156:159], v193, s[16:17]
	s_barrier
; __device__ __forceinline__ void sb_decode_stream(Frame& F, unsigned* qctr, int base, int limit) {
;     ...
;         f32x4 o4 = {0.f, 0.f, 0.f, 0.f};
; #pragma unroll
;         for (int i = 0; i < 16; ++i) { const float aj = __shfl(a, 2 * i + half); o4 += aj * A[i]; }
;         const f32x4 q4n = *(const f32x4*)(SSP(S_PROJ) + (size_t)bn * IN_COLS + hn * HD + 4 * l32);
; #pragma unroll
;         for (int i = 0; i < 16; ++i) A[i] = __builtin_nontemporal_load((const f32x4*)(CK + cbn + (size_t)(2 * i) * stepn));
; #pragma unroll
;         for (int i = 0; i < 16; ++i) { const float aj = __shfl(a, 32 + 2 * i + half); o4 += aj * B[i]; }
; #pragma unroll
;         for (int i = 0; i < 16; ++i) B[i] = __builtin_nontemporal_load((const f32x4*)(CK + cbn + (size_t)(32 + 2 * i) * stepn));
	v_mov_b32_e32 v160, 0
	v_mov_b32_e32 v161, 0
	v_mov_b32_e32 v162, 0
	v_mov_b32_e32 v163, 0
	v_mov_b32_e32 v164, 0
	v_mov_b32_e32 v165, 0
	v_mov_b32_e32 v166, 0
	v_mov_b32_e32 v167, 0
	ds_bpermute_b32 v168, v188, v186 offset:0
	ds_bpermute_b32 v170, v188, v186 offset:4
	ds_bpermute_b32 v172, v188, v186 offset:8
	ds_bpermute_b32 v174, v188, v186 offset:12
	s_waitcnt vmcnt(32) lgkmcnt(3)
	v_pk_fma_f32 v[160:161], v[4:5], v[168:169], v[160:161] op_sel_hi:[1,0,1]
	v_pk_fma_f32 v[162:163], v[6:7], v[168:169], v[162:163] op_sel_hi:[1,0,1]
	global_load_dwordx4 v[4:7], v187, s[64:65] nt
	s_add_u32 s64, s64, 0x2000
	s_addc_u32 s65, s65, 0
	ds_bpermute_b32 v168, v188, v186 offset:16
	s_waitcnt vmcnt(32) lgkmcnt(3)
	v_pk_fma_f32 v[164:165], v[8:9], v[170:171], v[164:165] op_sel_hi:[1,0,1]
	v_pk_fma_f32 v[166:167], v[10:11], v[170:171], v[166:167] op_sel_hi:[1,0,1]
	global_load_dwordx4 v[8:11], v187, s[64:65] nt
	s_add_u32 s64, s64, 0x2000
	s_addc_u32 s65, s65, 0
	ds_bpermute_b32 v170, v188, v186 offset:20
	s_waitcnt vmcnt(32) lgkmcnt(3)
	v_pk_fma_f32 v[160:161], v[12:13], v[172:173], v[160:161] op_sel_hi:[1,0,1]
	v_pk_fma_f32 v[162:163], v[14:15], v[172:173], v[162:163] op_sel_hi:[1,0,1]
	global_load_dwordx4 v[12:15], v187, s[64:65] nt
	s_add_u32 s64, s64, 0x2000
	s_addc_u32 s65, s65, 0
	ds_bpermute_b32 v172, v188, v186 offset:24
	s_waitcnt vmcnt(32) lgkmcnt(3)
	v_pk_fma_f32 v[164:165], v[16:17], v[174:175], v[164:165] op_sel_hi:[1,0,1]
	v_pk_fma_f32 v[166:167], v[18:19], v[174:175], v[166:167] op_sel_hi:[1,0,1]
	global_load_dwordx4 v[16:19], v187, s[64:65] nt
	s_add_u32 s64, s64, 0x2000
	s_addc_u32 s65, s65, 0
	ds_bpermute_b32 v174, v188, v186 offset:28
	s_waitcnt vmcnt(32) lgkmcnt(3)
	v_pk_fma_f32 v[160:161], v[20:21], v[168:169], v[160:161] op_sel_hi:[1,0,1]
	v_pk_fma_f32 v[162:163], v[22:23], v[168:169], v[162:163] op_sel_hi:[1,0,1]
	global_load_dwordx4 v[20:23], v187, s[64:65] nt
	s_add_u32 s64, s64, 0x2000
	s_addc_u32 s65, s65, 0
	ds_bpermute_b32 v168, v188, v186 offset:32
	s_waitcnt vmcnt(32) lgkmcnt(3)
	v_pk_fma_f32 v[164:165], v[24:25], v[170:171], v[164:165] op_sel_hi:[1,0,1]
	v_pk_fma_f32 v[166:167], v[26:27], v[170:171], v[166:167] op_sel_hi:[1,0,1]
	global_load_dwordx4 v[24:27], v187, s[64:65] nt
	s_add_u32 s64, s64, 0x2000
	s_addc_u32 s65, s65, 0
	ds_bpermute_b32 v170, v188, v186 offset:36
	s_waitcnt vmcnt(32) lgkmcnt(3)
	v_pk_fma_f32 v[160:161], v[28:29], v[172:173], v[160:161] op_sel_hi:[1,0,1]
	v_pk_fma_f32 v[162:163], v[30:31], v[172:173], v[162:163] op_sel_hi:[1,0,1]
	global_load_dwordx4 v[28:31], v187, s[64:65] nt
	s_add_u32 s64, s64, 0x2000
	s_addc_u32 s65, s65, 0
	ds_bpermute_b32 v172, v188, v186 offset:40
	s_waitcnt vmcnt(32) lgkmcnt(3)
	v_pk_fma_f32 v[164:165], v[32:33], v[174:175], v[164:165] op_sel_hi:[1,0,1]
	v_pk_fma_f32 v[166:167], v[34:35], v[174:175], v[166:167] op_sel_hi:[1,0,1]
	global_load_dwordx4 v[32:35], v187, s[64:65] nt
	s_add_u32 s64, s64, 0x2000
	s_addc_u32 s65, s65, 0
	ds_bpermute_b32 v174, v188, v186 offset:44
	s_waitcnt vmcnt(32) lgkmcnt(3)
	v_pk_fma_f32 v[160:161], v[36:37], v[168:169], v[160:161] op_sel_hi:[1,0,1]
	v_pk_fma_f32 v[162:163], v[38:39], v[168:169], v[162:163] op_sel_hi:[1,0,1]
	global_load_dwordx4 v[36:39], v187, s[64:65] nt
	s_add_u32 s64, s64, 0x2000
	s_addc_u32 s65, s65, 0
	ds_bpermute_b32 v168, v188, v186 offset:48
	s_waitcnt vmcnt(32) lgkmcnt(3)
	v_pk_fma_f32 v[164:165], v[40:41], v[170:171], v[164:165] op_sel_hi:[1,0,1]
	v_pk_fma_f32 v[166:167], v[42:43], v[170:171], v[166:167] op_sel_hi:[1,0,1]
	global_load_dwordx4 v[40:43], v187, s[64:65] nt
	s_add_u32 s64, s64, 0x2000
	s_addc_u32 s65, s65, 0
	ds_bpermute_b32 v170, v188, v186 offset:52
	s_waitcnt vmcnt(32) lgkmcnt(3)
	v_pk_fma_f32 v[160:161], v[44:45], v[172:173], v[160:161] op_sel_hi:[1,0,1]
	v_pk_fma_f32 v[162:163], v[46:47], v[172:173], v[162:163] op_sel_hi:[1,0,1]
	global_load_dwordx4 v[44:47], v187, s[64:65] nt
	s_add_u32 s64, s64, 0x2000
	s_addc_u32 s65, s65, 0
	ds_bpermute_b32 v172, v188, v186 offset:56
	s_waitcnt vmcnt(32) lgkmcnt(3)
	v_pk_fma_f32 v[164:165], v[48:49], v[174:175], v[164:165] op_sel_hi:[1,0,1]
	v_pk_fma_f32 v[166:167], v[50:51], v[174:175], v[166:167] op_sel_hi:[1,0,1]
	global_load_dwordx4 v[48:51], v187, s[64:65] nt
	s_add_u32 s64, s64, 0x2000
	s_addc_u32 s65, s65, 0
	ds_bpermute_b32 v174, v188, v186 offset:60
	s_waitcnt vmcnt(32) lgkmcnt(3)
	v_pk_fma_f32 v[160:161], v[52:53], v[168:169], v[160:161] op_sel_hi:[1,0,1]
	v_pk_fma_f32 v[162:163], v[54:55], v[168:169], v[162:163] op_sel_hi:[1,0,1]
	global_load_dwordx4 v[52:55], v187, s[64:65] nt
	s_add_u32 s64, s64, 0x2000
	s_addc_u32 s65, s65, 0
	ds_bpermute_b32 v168, v188, v186 offset:64
	s_waitcnt vmcnt(32) lgkmcnt(3)
	v_pk_fma_f32 v[164:165], v[56:57], v[170:171], v[164:165] op_sel_hi:[1,0,1]
	v_pk_fma_f32 v[166:167], v[58:59], v[170:171], v[166:167] op_sel_hi:[1,0,1]
	global_load_dwordx4 v[56:59], v187, s[64:65] nt
	s_add_u32 s64, s64, 0x2000
	s_addc_u32 s65, s65, 0
	ds_bpermute_b32 v170, v188, v186 offset:68
	s_waitcnt vmcnt(32) lgkmcnt(3)
	v_pk_fma_f32 v[160:161], v[60:61], v[172:173], v[160:161] op_sel_hi:[1,0,1]
	v_pk_fma_f32 v[162:163], v[62:63], v[172:173], v[162:163] op_sel_hi:[1,0,1]
	global_load_dwordx4 v[60:63], v187, s[64:65] nt
	s_add_u32 s64, s64, 0x2000
	s_addc_u32 s65, s65, 0
	ds_bpermute_b32 v172, v188, v186 offset:72
	s_waitcnt vmcnt(32) lgkmcnt(3)
	v_pk_fma_f32 v[164:165], v[64:65], v[174:175], v[164:165] op_sel_hi:[1,0,1]
	v_pk_fma_f32 v[166:167], v[66:67], v[174:175], v[166:167] op_sel_hi:[1,0,1]
	global_load_dwordx4 v[64:67], v187, s[64:65] nt
	s_add_u32 s64, s64, 0x2000
	s_addc_u32 s65, s65, 0
	ds_bpermute_b32 v174, v188, v186 offset:76
	s_waitcnt vmcnt(32) lgkmcnt(3)
; __device__ __forceinline__ void sb_decode_stream(Frame& F, unsigned* qctr, int base, int limit) {
;     ...
;         f32x4 o4 = {0.f, 0.f, 0.f, 0.f};
; #pragma unroll
;         for (int i = 0; i < 16; ++i) { const float aj = __shfl(a, 2 * i + half); o4 += aj * A[i]; }
;         const f32x4 q4n = *(const f32x4*)(SSP(S_PROJ) + (size_t)bn * IN_COLS + hn * HD + 4 * l32);
; #pragma unroll
;         for (int i = 0; i < 16; ++i) A[i] = __builtin_nontemporal_load((const f32x4*)(CK + cbn + (size_t)(2 * i) * stepn));
; #pragma unroll
;         for (int i = 0; i < 16; ++i) { const float aj = __shfl(a, 32 + 2 * i + half); o4 += aj * B[i]; }
; #pragma unroll
;         for (int i = 0; i < 16; ++i) B[i] = __builtin_nontemporal_load((const f32x4*)(CK + cbn + (size_t)(32 + 2 * i) * stepn));
;         o4.x += __shfl_xor(o4.x, 32); o4.y += __shfl_xor(o4.y, 32); o4.z += __shfl_xor(o4.z, 32); o4.w += __shfl_xor(o4.w, 32);
;         float* P = SSP(S_PART) + ((size_t)bh * DSEG + blk) * DPART;
;         if (half == 0) *(f32x4*)(P + 4 * l32) = o4; if (lane == 0) P[128] = tot;
;         if (!more) break;
;         it = itn; cb = cbn; q4 = q4n;
	v_pk_fma_f32 v[160:161], v[68:69], v[168:169], v[160:161] op_sel_hi:[1,0,1]
	v_pk_fma_f32 v[162:163], v[70:71], v[168:169], v[162:163] op_sel_hi:[1,0,1]
	global_load_dwordx4 v[68:71], v187, s[64:65] nt
	s_add_u32 s64, s64, 0x2000
	s_addc_u32 s65, s65, 0
	ds_bpermute_b32 v168, v188, v186 offset:80
	s_waitcnt vmcnt(32) lgkmcnt(3)
	v_pk_fma_f32 v[164:165], v[72:73], v[170:171], v[164:165] op_sel_hi:[1,0,1]
	v_pk_fma_f32 v[166:167], v[74:75], v[170:171], v[166:167] op_sel_hi:[1,0,1]
	global_load_dwordx4 v[72:75], v187, s[64:65] nt
	s_add_u32 s64, s64, 0x2000
	s_addc_u32 s65, s65, 0
	ds_bpermute_b32 v170, v188, v186 offset:84
	s_waitcnt vmcnt(32) lgkmcnt(3)
	v_pk_fma_f32 v[160:161], v[76:77], v[172:173], v[160:161] op_sel_hi:[1,0,1]
	v_pk_fma_f32 v[162:163], v[78:79], v[172:173], v[162:163] op_sel_hi:[1,0,1]
	global_load_dwordx4 v[76:79], v187, s[64:65] nt
	s_add_u32 s64, s64, 0x2000
	s_addc_u32 s65, s65, 0
	ds_bpermute_b32 v172, v188, v186 offset:88
	s_waitcnt vmcnt(32) lgkmcnt(3)
	v_pk_fma_f32 v[164:165], v[80:81], v[174:175], v[164:165] op_sel_hi:[1,0,1]
	v_pk_fma_f32 v[166:167], v[82:83], v[174:175], v[166:167] op_sel_hi:[1,0,1]
	global_load_dwordx4 v[80:83], v187, s[64:65] nt
	s_add_u32 s64, s64, 0x2000
	s_addc_u32 s65, s65, 0
	ds_bpermute_b32 v174, v188, v186 offset:92
	s_waitcnt vmcnt(32) lgkmcnt(3)
	v_pk_fma_f32 v[160:161], v[84:85], v[168:169], v[160:161] op_sel_hi:[1,0,1]
	v_pk_fma_f32 v[162:163], v[86:87], v[168:169], v[162:163] op_sel_hi:[1,0,1]
	global_load_dwordx4 v[84:87], v187, s[64:65] nt
	s_add_u32 s64, s64, 0x2000
	s_addc_u32 s65, s65, 0
	ds_bpermute_b32 v168, v188, v186 offset:96
	s_waitcnt vmcnt(32) lgkmcnt(3)
	v_pk_fma_f32 v[164:165], v[88:89], v[170:171], v[164:165] op_sel_hi:[1,0,1]
	v_pk_fma_f32 v[166:167], v[90:91], v[170:171], v[166:167] op_sel_hi:[1,0,1]
	global_load_dwordx4 v[88:91], v187, s[64:65] nt
	s_add_u32 s64, s64, 0x2000
	s_addc_u32 s65, s65, 0
	ds_bpermute_b32 v170, v188, v186 offset:100
	s_waitcnt vmcnt(32) lgkmcnt(3)
	v_pk_fma_f32 v[160:161], v[92:93], v[172:173], v[160:161] op_sel_hi:[1,0,1]
	v_pk_fma_f32 v[162:163], v[94:95], v[172:173], v[162:163] op_sel_hi:[1,0,1]
	global_load_dwordx4 v[92:95], v187, s[64:65] nt
	s_add_u32 s64, s64, 0x2000
	s_addc_u32 s65, s65, 0
	ds_bpermute_b32 v172, v188, v186 offset:104
	s_waitcnt vmcnt(32) lgkmcnt(3)
	v_pk_fma_f32 v[164:165], v[96:97], v[174:175], v[164:165] op_sel_hi:[1,0,1]
	v_pk_fma_f32 v[166:167], v[98:99], v[174:175], v[166:167] op_sel_hi:[1,0,1]
	global_load_dwordx4 v[96:99], v187, s[64:65] nt
	s_add_u32 s64, s64, 0x2000
	s_addc_u32 s65, s65, 0
	ds_bpermute_b32 v174, v188, v186 offset:108
	s_waitcnt vmcnt(32) lgkmcnt(3)
	v_pk_fma_f32 v[160:161], v[100:101], v[168:169], v[160:161] op_sel_hi:[1,0,1]
	v_pk_fma_f32 v[162:163], v[102:103], v[168:169], v[162:163] op_sel_hi:[1,0,1]
	global_load_dwordx4 v[100:103], v187, s[64:65] nt
	s_add_u32 s64, s64, 0x2000
	s_addc_u32 s65, s65, 0
	ds_bpermute_b32 v168, v188, v186 offset:112
	s_waitcnt vmcnt(32) lgkmcnt(3)
	v_pk_fma_f32 v[164:165], v[104:105], v[170:171], v[164:165] op_sel_hi:[1,0,1]
	v_pk_fma_f32 v[166:167], v[106:107], v[170:171], v[166:167] op_sel_hi:[1,0,1]
	global_load_dwordx4 v[104:107], v187, s[64:65] nt
	s_add_u32 s64, s64, 0x2000
	s_addc_u32 s65, s65, 0
	ds_bpermute_b32 v170, v188, v186 offset:116
	s_waitcnt vmcnt(32) lgkmcnt(3)
	v_pk_fma_f32 v[160:161], v[108:109], v[172:173], v[160:161] op_sel_hi:[1,0,1]
	v_pk_fma_f32 v[162:163], v[110:111], v[172:173], v[162:163] op_sel_hi:[1,0,1]
	global_load_dwordx4 v[108:111], v187, s[64:65] nt
	s_add_u32 s64, s64, 0x2000
	s_addc_u32 s65, s65, 0
	ds_bpermute_b32 v172, v188, v186 offset:120
	s_waitcnt vmcnt(32) lgkmcnt(3)
	v_pk_fma_f32 v[164:165], v[112:113], v[174:175], v[164:165] op_sel_hi:[1,0,1]
	v_pk_fma_f32 v[166:167], v[114:115], v[174:175], v[166:167] op_sel_hi:[1,0,1]
	global_load_dwordx4 v[112:115], v187, s[64:65] nt
	s_add_u32 s64, s64, 0x2000
	s_addc_u32 s65, s65, 0
	ds_bpermute_b32 v174, v188, v186 offset:124
	s_waitcnt vmcnt(32) lgkmcnt(3)
	v_pk_fma_f32 v[160:161], v[116:117], v[168:169], v[160:161] op_sel_hi:[1,0,1]
	v_pk_fma_f32 v[162:163], v[118:119], v[168:169], v[162:163] op_sel_hi:[1,0,1]
	global_load_dwordx4 v[116:119], v187, s[64:65] nt
	s_add_u32 s64, s64, 0x2000
	s_addc_u32 s65, s65, 0
	s_waitcnt vmcnt(32) lgkmcnt(2)
	v_pk_fma_f32 v[164:165], v[120:121], v[170:171], v[164:165] op_sel_hi:[1,0,1]
	v_pk_fma_f32 v[166:167], v[122:123], v[170:171], v[166:167] op_sel_hi:[1,0,1]
	global_load_dwordx4 v[120:123], v187, s[64:65] nt
	s_add_u32 s64, s64, 0x2000
	s_addc_u32 s65, s65, 0
	s_waitcnt vmcnt(32) lgkmcnt(1)
	v_pk_fma_f32 v[160:161], v[124:125], v[172:173], v[160:161] op_sel_hi:[1,0,1]
	v_pk_fma_f32 v[162:163], v[126:127], v[172:173], v[162:163] op_sel_hi:[1,0,1]
	global_load_dwordx4 v[124:127], v187, s[64:65] nt
	s_add_u32 s64, s64, 0x2000
	s_addc_u32 s65, s65, 0
	s_waitcnt vmcnt(32) lgkmcnt(0)
	v_pk_fma_f32 v[164:165], v[128:129], v[174:175], v[164:165] op_sel_hi:[1,0,1]
	v_pk_fma_f32 v[166:167], v[130:131], v[174:175], v[166:167] op_sel_hi:[1,0,1]
	global_load_dwordx4 v[128:131], v187, s[64:65] nt
	s_add_u32 s64, s64, 0x2000
	s_addc_u32 s65, s65, 0
	s_nop 1
	v_pk_add_f32 v[160:161], v[160:161], v[164:165]
	v_pk_add_f32 v[162:163], v[162:163], v[166:167]
	s_nop 1
	v_mov_b32_e32 v164, v160
	v_mov_b32_e32 v165, v161
	v_mov_b32_e32 v166, v162
	v_mov_b32_e32 v167, v163
	v_permlane32_swap_b32_e32 v160, v164
	v_permlane32_swap_b32_e32 v161, v165
	v_permlane32_swap_b32_e32 v162, v166
	v_permlane32_swap_b32_e32 v163, v167
	v_pk_add_f32 v[160:161], v[160:161], v[164:165]
	v_pk_add_f32 v[162:163], v[162:163], v[166:167]
	s_nop 1
	s_mov_b32 exec_hi, 0
	global_store_dwordx4 v193, v[160:163], s[70:71]
	s_mov_b32 exec_lo, 1
	global_store_dword v189, v183, s[70:71] offset:512
	s_mov_b64 exec, -1
	s_mov_b32 s72, s73
	s_branch .Ldqc_loop
